# mLSTM-out loop: CO/CZ gate rows requested at unit top ahead of the next unit's prefetch; counted vmcnt (0/8/14) before the second barrier leaves the prefetch in flight
# baseline (speedup 1.0000x reference)
; #define LAS __attribute__((address_space(3)))
; #define LDS_WAIT() asm volatile("s_waitcnt lgkmcnt(0)" ::: "memory")
; __device__ __forceinline__ int crow(int r, int hi) { return (r & 3) + 8 * (r >> 2) + 4 * hi; }
; __device__ __forceinline__ void mlstm_out_loop(unsigned char* ws, h16* Y, const float* ghead  , int u  , const int o_mout, const int o_end, const int ntc, const bool ctx_out, ...
;     ...
;         const float hden = fmaxf(fabsf(sacc), __builtin_amdgcn_exp2f(-(bt + Mt) * LOG2E));
;         LAS float* wsf = (LAS float*)(lds + MO_WS) + wid * 64;
;         if (hi == 0) wsf[r32] = __builtin_amdgcn_rcpf(hden);
;         LDS_WAIT();
;         LAS h16* ost = (LAS h16*)(lds + MO_OST) + wid * 2048;
; #pragma unroll
;         for (int r = 0; r < 16; ++r) { const int orow = crow(r, hi); const float rl = wsf[orow];
; #pragma unroll
;             for (int d0 = 0; d0 < 2; ++d0) ost[orow * 64 + d0 * 32 + r32] = (h16)(o[d0][r] * rl); }
.LBB0_391:
	s_or_b64 exec, exec, s[0:1]
	s_waitcnt lgkmcnt(0)
	v_add_u32_e32 v34, 0x9400, v180
	ds_read2_b32 v[34:35], v34 offset1:1
	s_and_b64 vcc, exec, s[6:7]
	s_cbranch_vccnz .Lmo_w0
	s_and_b64 vcc, exec, s[36:37]
	s_cbranch_vccz .Lmo_w8
	s_waitcnt vmcnt(14)
	s_branch .Lmo_wd
.Lmo_w8:
	s_waitcnt vmcnt(8)
	s_branch .Lmo_wd

; #define LAS __attribute__((address_space(3)))
; __device__ __forceinline__ float siluf(float x) { return x * __builtin_amdgcn_rcpf(1.f + __builtin_amdgcn_exp2f(-1.4426950408889634f * x)); }
; __device__ __forceinline__ float sigmf(float x) { return __builtin_amdgcn_rcpf(1.f + __builtin_amdgcn_exp2f(-1.4426950408889634f * x)); }
; __device__ __forceinline__ float oct_sum(float s) { s += dpp_f<0xB1>(s); s += dpp_f<0x4E>(s); s += dpp_f<0x141>(s); return s; }
; #define BAR_LDS() asm volatile("s_waitcnt lgkmcnt(0)\n\ts_barrier" ::: "memory")
; __device__ __forceinline__ int crow(int r, int hi) { return (r & 3) + 8 * (r >> 2) + 4 * hi; }
; __device__ __forceinline__ void mlstm_out_loop(unsigned char* ws, h16* Y, const float* ghead  , int u  , const int o_mout, const int o_end, const int ntc, const bool ctx_out, ...
;     ...
;         LAS h16* ost = (LAS h16*)(lds + MO_OST) + wid * 2048;
; #pragma unroll
;         for (int r = 0; r < 16; ++r) { const int orow = crow(r, hi); const float rl = wsf[orow];
; #pragma unroll
;             for (int d0 = 0; d0 < 2; ++d0) ost[orow * 64 + d0 * 32 + r32] = (h16)(o[d0][r] * rl); }
;         BAR_LDS();
; #pragma unroll
;         for (int ps = 0; ps < 2; ++ps) { const int row = 64 * ps + frow, wt = row >> 5, tr = row & 31; const LAS h16* pf = (const LAS h16*)(lds + MO_OST) + wt * 2048 + tr * 64 + fc8 * 8; const LAS h16* pb = pf + 4 * 2048;
;           const h16x8 af = *(const LAS h16x8*)pf, ab = *(const LAS h16x8*)pb;
;           float x[8]; float ss = 0.f;
; #pragma unroll
;           for (int j = 0; j < 8; ++j) { x[j] = (float)af[j] + (float)ab[j]; ss += x[j] * x[j]; }
;           ss = oct_sum(ss);
;           const float rn = __builtin_amdgcn_rsqf(ss * (1.f / 64.f) + EPS); const LAS float* gh = (const LAS float*)(lds + MO_GH) + h * 64 + fc8 * 8;
;           const h16x8 co = ps ? co1 : co0, cz = ps ? cz1 : cz0;
;           float y[8];
; #pragma unroll
;           for (int j = 0; j < 8; ++j) y[j] = sigmf((float)co[j]) * (x[j] * rn * gh[j]) * siluf((float)cz[j]);
.Lmo_wd:
	v_cvt_f32_f16_e32 v38, v106
	v_cvt_f32_f16_sdwa v39, v106 dst_sel:DWORD dst_unused:UNUSED_PAD src0_sel:WORD_1
	v_readlane_b32 s44, v251, 0
	v_readlane_b32 s45, v251, 1
	s_waitcnt lgkmcnt(0)
	v_fma_mixlo_f16 v2, v2, v34, 0
	ds_write_b16 v193, v2 offset:40960
	v_fma_mixlo_f16 v2, v18, v34, 0
	ds_write_b16 v193, v2 offset:41024
	v_fma_mixlo_f16 v2, v3, v35, 0
	ds_write_b16 v194, v2 offset:40960
	v_fma_mixlo_f16 v2, v19, v35, 0
	ds_write_b16 v194, v2 offset:41024
	v_add_u32_e32 v2, 0x9408, v180
	ds_read2_b32 v[2:3], v2 offset1:1
	s_mov_b32 s21, s40
	s_and_b64 vcc, exec, s[6:7]
	s_mov_b32 s76, s25
	v_readlane_b32 s46, v251, 2
	s_waitcnt lgkmcnt(0)
	v_fma_mixlo_f16 v4, v4, v2, 0
	v_fma_mixlo_f16 v2, v20, v2, 0
	ds_write_b16 v195, v2 offset:41024
	v_fma_mixlo_f16 v2, v5, v3, 0
	ds_write_b16 v196, v2 offset:40960
	v_fma_mixlo_f16 v2, v21, v3, 0
	ds_write_b16 v196, v2 offset:41024
	v_add_u32_e32 v2, 0x9420, v180
	ds_read2_b32 v[2:3], v2 offset1:1
	ds_write_b16 v195, v4 offset:40960
	v_readlane_b32 s47, v251, 3
	v_readlane_b32 s48, v251, 4
	v_readlane_b32 s49, v251, 5
	s_waitcnt lgkmcnt(1)
	v_fma_mixlo_f16 v4, v6, v2, 0
	v_fma_mixlo_f16 v2, v22, v2, 0
	ds_write_b16 v197, v2 offset:41024
	v_fma_mixlo_f16 v2, v7, v3, 0
	ds_write_b16 v198, v2 offset:40960
	v_fma_mixlo_f16 v2, v23, v3, 0
	ds_write_b16 v198, v2 offset:41024
	v_add_u32_e32 v2, 0x9428, v180
	ds_read2_b32 v[2:3], v2 offset1:1
	ds_write_b16 v197, v4 offset:40960
	v_readlane_b32 s50, v251, 6
	v_readlane_b32 s51, v251, 7
	s_waitcnt lgkmcnt(1)
	v_fma_mixlo_f16 v4, v8, v2, 0
	v_fma_mixlo_f16 v2, v24, v2, 0
	ds_write_b16 v199, v2 offset:41024
	v_fma_mixlo_f16 v2, v9, v3, 0
	ds_write_b16 v200, v2 offset:40960
	v_fma_mixlo_f16 v2, v25, v3, 0
	ds_write_b16 v200, v2 offset:41024
	v_add_u32_e32 v2, 0x9440, v180
	ds_read2_b32 v[2:3], v2 offset1:1
	ds_write_b16 v199, v4 offset:40960
	s_waitcnt lgkmcnt(1)
	v_fma_mixlo_f16 v4, v10, v2, 0
	v_fma_mixlo_f16 v2, v26, v2, 0
	ds_write_b16 v201, v2 offset:41024
	v_fma_mixlo_f16 v2, v11, v3, 0
	ds_write_b16 v202, v2 offset:40960
	v_fma_mixlo_f16 v2, v27, v3, 0
	ds_write_b16 v202, v2 offset:41024
	v_add_u32_e32 v2, 0x9448, v180
	ds_read2_b32 v[2:3], v2 offset1:1
	ds_write_b16 v201, v4 offset:40960
	v_cvt_f32_f16_e32 v10, v110
	s_waitcnt lgkmcnt(1)
	v_fma_mixlo_f16 v4, v12, v2, 0
	v_fma_mixlo_f16 v2, v28, v2, 0
	ds_write_b16 v203, v2 offset:41024
	v_fma_mixlo_f16 v2, v13, v3, 0
	ds_write_b16 v204, v2 offset:40960
	v_fma_mixlo_f16 v2, v29, v3, 0
	ds_write_b16 v204, v2 offset:41024
	v_add_u32_e32 v2, 0x9460, v180
	ds_read2_b32 v[2:3], v2 offset1:1
	ds_write_b16 v203, v4 offset:40960
	v_mul_f32_e32 v10, 0xbfb8aa3b, v10
	v_exp_f32_e32 v10, v10
	v_lshl_add_u32 v28, s20, 2, v164
	s_waitcnt lgkmcnt(1)
	v_fma_mixlo_f16 v4, v14, v2, 0
	v_fma_mixlo_f16 v2, v30, v2, 0
	ds_write_b16 v205, v2 offset:41024
	v_fma_mixlo_f16 v2, v15, v3, 0
	ds_write_b16 v206, v2 offset:40960
	v_fma_mixlo_f16 v2, v31, v3, 0
	ds_write_b16 v206, v2 offset:41024
	v_add_u32_e32 v2, 0x9468, v180
	ds_read2_b32 v[2:3], v2 offset1:1
	v_add_f32_e32 v10, 1.0, v10
	ds_write_b16 v205, v4 offset:40960
	v_mul_f32_e32 v29, 0xbfb8aa3b, v39
	v_exp_f32_e32 v29, v29
	s_waitcnt lgkmcnt(1)
	v_fma_mixlo_f16 v4, v16, v2, 0
	v_rcp_f32_e32 v16, v10
	v_cvt_f32_f16_sdwa v10, v110 dst_sel:DWORD dst_unused:UNUSED_PAD src0_sel:WORD_1
	v_fma_mixlo_f16 v2, v32, v2, 0
	ds_write_b16 v207, v2 offset:41024
	v_fma_mixlo_f16 v2, v17, v3, 0
	v_mul_f32_e32 v10, 0xbfb8aa3b, v10
	v_exp_f32_e32 v10, v10
	ds_write_b16 v213, v2 offset:40960
	v_fma_mixlo_f16 v2, v33, v3, 0
	ds_write_b16 v207, v4 offset:40960
	v_add_f32_e32 v10, 1.0, v10
	v_rcp_f32_e32 v17, v10
	v_cvt_f32_f16_e32 v10, v111
	ds_write_b16 v213, v2 offset:41024
	s_waitcnt lgkmcnt(0)
	s_barrier
	ds_read_b128 v[6:9], v181 offset:40960
	ds_read_b128 v[2:5], v181 offset:57344
	v_mul_f32_e32 v10, 0xbfb8aa3b, v10
	v_exp_f32_e32 v10, v10
	v_add_f32_e32 v29, 1.0, v29
	s_waitcnt lgkmcnt(1)
	v_cvt_f32_f16_sdwa v11, v9 dst_sel:DWORD dst_unused:UNUSED_PAD src0_sel:WORD_1
	s_waitcnt lgkmcnt(0)
	v_cvt_f32_f16_sdwa v13, v5 dst_sel:DWORD dst_unused:UNUSED_PAD src0_sel:WORD_1
	v_add_f32_e32 v10, 1.0, v10
	v_rcp_f32_e32 v18, v10
	v_cvt_f32_f16_sdwa v10, v111 dst_sel:DWORD dst_unused:UNUSED_PAD src0_sel:WORD_1
	v_cvt_f32_f16_e32 v12, v5
	v_cvt_f32_f16_sdwa v5, v4 dst_sel:DWORD dst_unused:UNUSED_PAD src0_sel:WORD_1
	v_cvt_f32_f16_e32 v4, v4
	v_mul_f32_e32 v10, 0xbfb8aa3b, v10
	v_exp_f32_e32 v10, v10
	v_rcp_f32_e32 v41, v29
	s_lshl_b32 s20, s20, 1
	v_add_f32_e32 v10, 1.0, v10
	v_rcp_f32_e32 v19, v10
	v_cvt_f32_f16_e32 v10, v112
	v_mul_f32_e32 v10, 0xbfb8aa3b, v10
	v_exp_f32_e32 v10, v10
	s_nop 0
	v_add_f32_e32 v10, 1.0, v10
	v_rcp_f32_e32 v22, v10
	v_cvt_f32_f16_sdwa v10, v112 dst_sel:DWORD dst_unused:UNUSED_PAD src0_sel:WORD_1
	v_mul_f32_e32 v10, 0xbfb8aa3b, v10
	v_exp_f32_e32 v10, v10
	s_nop 0
	v_add_f32_e32 v10, 1.0, v10
	v_rcp_f32_e32 v23, v10
	v_cvt_f32_f16_e32 v10, v113
	v_mul_f32_e32 v10, 0xbfb8aa3b, v10
	v_exp_f32_e32 v10, v10
	s_nop 0
	v_add_f32_e32 v10, 1.0, v10
	v_rcp_f32_e32 v20, v10
	v_cvt_f32_f16_sdwa v10, v113 dst_sel:DWORD dst_unused:UNUSED_PAD src0_sel:WORD_1
	v_mul_f32_e32 v10, 0xbfb8aa3b, v10
	v_exp_f32_e32 v10, v10
	s_nop 0
	v_add_f32_e32 v10, 1.0, v10
	v_rcp_f32_e32 v21, v10
	v_cvt_f32_f16_e32 v10, v9
	v_cvt_f32_f16_sdwa v9, v8 dst_sel:DWORD dst_unused:UNUSED_PAD src0_sel:WORD_1
	v_cvt_f32_f16_e32 v8, v8
	v_pk_add_f32 v[24:25], v[10:11], v[12:13]
	v_cvt_f32_f16_sdwa v13, v108 dst_sel:DWORD dst_unused:UNUSED_PAD src0_sel:WORD_1
	v_cvt_f32_f16_e32 v12, v108
	v_pk_add_f32 v[8:9], v[8:9], v[4:5]
	v_pk_mul_f32 v[26:27], v[24:25], v[24:25]
	v_mul_f32_e32 v15, 0xbfb8aa3b, v13
; #define LAS __attribute__((address_space(3)))
; #define GAS __attribute__((address_space(1)))
; __device__ __forceinline__ float siluf(float x) { return x * __builtin_amdgcn_rcpf(1.f + __builtin_amdgcn_exp2f(-1.4426950408889634f * x)); }
; __device__ __forceinline__ float sigmf(float x) { return __builtin_amdgcn_rcpf(1.f + __builtin_amdgcn_exp2f(-1.4426950408889634f * x)); }
; __device__ __forceinline__ float oct_sum(float s) { s += dpp_f<0xB1>(s); s += dpp_f<0x4E>(s); s += dpp_f<0x141>(s); return s; }
; __device__ __forceinline__ unsigned cvtpk_h(float lo, float hi) { f32x2 v = {lo, hi}; h16x2 b = __builtin_convertvector(v, h16x2); return __builtin_bit_cast(unsigned, b); }
; __device__ __forceinline__ void mlstm_out_loop(unsigned char* ws, h16* Y, const float* ghead  , int u  , const int o_mout, const int o_end, const int ntc, const bool ctx_out, ...
;     ...
;         for (int ps = 0; ps < 2; ++ps) { const int row = 64 * ps + frow, wt = row >> 5, tr = row & 31; const LAS h16* pf = (const LAS h16*)(lds + MO_OST) + wt * 2048 + tr * 64 + fc8 * 8; const LAS h16* pb = pf + 4 * 2048;
;           const h16x8 af = *(const LAS h16x8*)pf, ab = *(const LAS h16x8*)pb;
;           float x[8]; float ss = 0.f;
; #pragma unroll
;           for (int j = 0; j < 8; ++j) { x[j] = (float)af[j] + (float)ab[j]; ss += x[j] * x[j]; }
;           ss = oct_sum(ss);
;           const float rn = __builtin_amdgcn_rsqf(ss * (1.f / 64.f) + EPS); const LAS float* gh = (const LAS float*)(lds + MO_GH) + h * 64 + fc8 * 8;
;           const h16x8 co = ps ? co1 : co0, cz = ps ? cz1 : cz0;
;           float y[8];
; #pragma unroll
;           for (int j = 0; j < 8; ++j) y[j] = sigmf((float)co[j]) * (x[j] * rn * gh[j]) * siluf((float)cz[j]);
;           u32x4 w0; w0.x = cvtpk_h(y[0], y[1]); w0.y = cvtpk_h(y[2], y[3]); w0.z = cvtpk_h(y[4], y[5]); w0.w = cvtpk_h(y[6], y[7]);
;           *(GAS u32x4*)(Y + (rb + row) * D + 768 + h * 64 + fc8 * 8) = w0; }
	v_mul_f32_e32 v10, 0xbfb8aa3b, v12
	v_exp_f32_e32 v10, v10
	v_exp_f32_e32 v15, v15
	v_pk_mul_f32 v[4:5], v[8:9], v[8:9]
	v_add_f32_e32 v10, 1.0, v10
	v_add_f32_e32 v15, 1.0, v15
	v_rcp_f32_e32 v14, v10
	v_rcp_f32_e32 v15, v15
	ds_read2_b32 v[10:11], v28 offset0:4 offset1:5
	v_pk_mul_f32 v[30:31], v[14:15], v[12:13]
	v_cvt_f32_f16_sdwa v13, v7 dst_sel:DWORD dst_unused:UNUSED_PAD src0_sel:WORD_1
	v_cvt_f32_f16_e32 v12, v7
	v_cvt_f32_f16_sdwa v15, v3 dst_sel:DWORD dst_unused:UNUSED_PAD src0_sel:WORD_1
	v_cvt_f32_f16_e32 v14, v3
	v_cvt_f32_f16_sdwa v7, v6 dst_sel:DWORD dst_unused:UNUSED_PAD src0_sel:WORD_1
	v_cvt_f32_f16_e32 v6, v6
	v_pk_add_f32 v[32:33], v[12:13], v[14:15]
	v_cvt_f32_f16_e32 v14, v107
	v_cvt_f32_f16_sdwa v15, v107 dst_sel:DWORD dst_unused:UNUSED_PAD src0_sel:WORD_1
	v_pk_mul_f32 v[34:35], v[32:33], v[32:33]
	ds_read2_b32 v[12:13], v28 offset0:2 offset1:3
	v_mul_f32_e32 v3, 0xbfb8aa3b, v14
	v_exp_f32_e32 v3, v3
	s_nop 0
	v_add_f32_e32 v3, 1.0, v3
	v_rcp_f32_e32 v36, v3
	v_mul_f32_e32 v3, 0xbfb8aa3b, v15
	v_exp_f32_e32 v3, v3
	s_nop 0
	v_add_f32_e32 v3, 1.0, v3
	v_rcp_f32_e32 v37, v3
	v_cvt_f32_f16_sdwa v3, v2 dst_sel:DWORD dst_unused:UNUSED_PAD src0_sel:WORD_1
	v_cvt_f32_f16_e32 v2, v2
	v_pk_mul_f32 v[36:37], v[36:37], v[14:15]
	v_mul_f32_e32 v14, 0xbfb8aa3b, v38
	v_pk_add_f32 v[2:3], v[6:7], v[2:3]
	v_exp_f32_e32 v14, v14
	v_pk_mul_f32 v[6:7], v[2:3], v[2:3]
	v_add_f32_e32 v14, 1.0, v14
	v_add_f32_e32 v6, v6, v7
	v_add_f32_e32 v6, v34, v6
	v_add_f32_e32 v6, v35, v6
	v_add_f32_e32 v4, v4, v6
	v_add_f32_e32 v4, v5, v4
	v_add_f32_e32 v4, v26, v4
	v_add_f32_e32 v4, v27, v4
	v_rcp_f32_e32 v40, v14
	ds_read2_b32 v[14:15], v28 offset1:1
	v_add_f32_dpp v4, v4, v4 quad_perm:[1,0,3,2] row_mask:0xf bank_mask:0xf bound_ctrl:1
	v_pk_mul_f32 v[38:39], v[40:41], v[38:39]
	s_nop 0
	v_add_f32_dpp v4, v4, v4 quad_perm:[2,3,0,1] row_mask:0xf bank_mask:0xf bound_ctrl:1
	s_nop 1
	v_add_f32_dpp v4, v4, v4 row_half_mirror row_mask:0xf bank_mask:0xf bound_ctrl:1
	v_fmamk_f32 v4, v4, 0x3c800000, v229
	v_rsq_f32_e32 v26, v4
	s_nop 0
	v_pk_mul_f32 v[6:7], v[8:9], v[26:27] op_sel_hi:[1,0]
	v_cvt_f32_f16_e32 v8, v109
	v_pk_mul_f32 v[2:3], v[2:3], v[26:27] op_sel_hi:[1,0]
	v_cvt_f32_f16_sdwa v9, v109 dst_sel:DWORD dst_unused:UNUSED_PAD src0_sel:WORD_1
	s_waitcnt lgkmcnt(0)
	v_pk_mul_f32 v[2:3], v[14:15], v[2:3]
	v_pk_mul_f32 v[4:5], v[32:33], v[26:27] op_sel_hi:[1,0]
	v_pk_mul_f32 v[2:3], v[16:17], v[2:3]
	v_mul_f32_e32 v16, 0xbfb8aa3b, v8
	v_pk_mul_f32 v[4:5], v[12:13], v[4:5]
	v_exp_f32_e32 v16, v16
	v_pk_mul_f32 v[4:5], v[18:19], v[4:5]
	v_mul_f32_e32 v19, 0xbfb8aa3b, v9
	v_exp_f32_e32 v19, v19
	v_add_f32_e32 v16, 1.0, v16
	v_rcp_f32_e32 v18, v16
	ds_read2_b32 v[16:17], v28 offset0:6 offset1:7
	v_add_f32_e32 v19, 1.0, v19
	v_pk_mul_f32 v[6:7], v[10:11], v[6:7]
	v_rcp_f32_e32 v19, v19
	v_pk_mul_f32 v[6:7], v[22:23], v[6:7]
	v_pk_mul_f32 v[2:3], v[38:39], v[2:3]
	v_pk_mul_f32 v[4:5], v[36:37], v[4:5]
	v_pk_mul_f32 v[6:7], v[30:31], v[6:7]
	v_pk_mul_f32 v[22:23], v[24:25], v[26:27] op_sel_hi:[1,0]
	v_cvt_pk_f16_f32 v2, v2, v3
	s_waitcnt lgkmcnt(0)
	v_pk_mul_f32 v[22:23], v[16:17], v[22:23]
	v_cvt_pk_f16_f32 v3, v4, v5
	v_cvt_pk_f16_f32 v4, v6, v7
	v_lshlrev_b64 v[6:7], 11, v[158:159]
	v_pk_mul_f32 v[20:21], v[20:21], v[22:23]
	v_pk_mul_f32 v[8:9], v[18:19], v[8:9]
	v_lshl_add_u64 v[6:7], s[44:45], 0, v[6:7]
	v_pk_mul_f32 v[8:9], v[8:9], v[20:21]
	v_lshl_add_u64 v[6:7], v[6:7], 0, s[20:21]
	v_cvt_pk_f16_f32 v5, v8, v9
	v_lshl_add_u64 v[6:7], v[6:7], 0, v[0:1]
	global_store_dwordx4 v[6:7], v[2:5], off offset:1536
	ds_read_b128 v[6:9], v182 offset:40960
	ds_read_b128 v[2:5], v182 offset:57344
	s_nop 0
	v_cvt_f32_f16_e32 v36, v99
	v_cvt_f32_f16_sdwa v31, v100 dst_sel:DWORD dst_unused:UNUSED_PAD src0_sel:WORD_1
	v_cvt_f32_f16_e32 v30, v100
	v_cvt_f32_f16_sdwa v37, v99 dst_sel:DWORD dst_unused:UNUSED_PAD src0_sel:WORD_1
	s_waitcnt lgkmcnt(0)
; #define LAS __attribute__((address_space(3)))
; #define GAS __attribute__((address_space(1)))
; __device__ __forceinline__ float siluf(float x) { return x * __builtin_amdgcn_rcpf(1.f + __builtin_amdgcn_exp2f(-1.4426950408889634f * x)); }
; __device__ __forceinline__ float sigmf(float x) { return __builtin_amdgcn_rcpf(1.f + __builtin_amdgcn_exp2f(-1.4426950408889634f * x)); }
; __device__ __forceinline__ float oct_sum(float s) { s += dpp_f<0xB1>(s); s += dpp_f<0x4E>(s); s += dpp_f<0x141>(s); return s; }
; __device__ __forceinline__ unsigned cvtpk_h(float lo, float hi) { f32x2 v = {lo, hi}; h16x2 b = __builtin_convertvector(v, h16x2); return __builtin_bit_cast(unsigned, b); }
; #define BAR_LDS() asm volatile("s_waitcnt lgkmcnt(0)\n\ts_barrier" ::: "memory")
; __device__ __forceinline__ void mlstm_out_loop(unsigned char* ws, h16* Y, const float* ghead  , int u  , const int o_mout, const int o_end, const int ntc, const bool ctx_out, ...
;     ...
;         for (int ps = 0; ps < 2; ++ps) { const int row = 64 * ps + frow, wt = row >> 5, tr = row & 31; const LAS h16* pf = (const LAS h16*)(lds + MO_OST) + wt * 2048 + tr * 64 + fc8 * 8; const LAS h16* pb = pf + 4 * 2048;
;           const h16x8 af = *(const LAS h16x8*)pf, ab = *(const LAS h16x8*)pb;
;           float x[8]; float ss = 0.f;
; #pragma unroll
;           for (int j = 0; j < 8; ++j) { x[j] = (float)af[j] + (float)ab[j]; ss += x[j] * x[j]; }
;           ss = oct_sum(ss);
;           const float rn = __builtin_amdgcn_rsqf(ss * (1.f / 64.f) + EPS); const LAS float* gh = (const LAS float*)(lds + MO_GH) + h * 64 + fc8 * 8;
;           const h16x8 co = ps ? co1 : co0, cz = ps ? cz1 : cz0;
;           float y[8];
; #pragma unroll
;           for (int j = 0; j < 8; ++j) y[j] = sigmf((float)co[j]) * (x[j] * rn * gh[j]) * siluf((float)cz[j]);
;           u32x4 w0; w0.x = cvtpk_h(y[0], y[1]); w0.y = cvtpk_h(y[2], y[3]); w0.z = cvtpk_h(y[4], y[5]); w0.w = cvtpk_h(y[6], y[7]);
;           *(GAS u32x4*)(Y + (rb + row) * D + 768 + h * 64 + fc8 * 8) = w0; }
;         BAR_LDS();
;         if (!more) break;
	v_cvt_f32_f16_sdwa v35, v3 dst_sel:DWORD dst_unused:UNUSED_PAD src0_sel:WORD_1
	v_cvt_f32_f16_e32 v34, v3
	v_mul_f32_e32 v3, 0xbfb8aa3b, v36
	v_exp_f32_e32 v3, v3
	v_mul_f32_e32 v32, 0xbfb8aa3b, v30
	v_mul_f32_e32 v33, 0xbfb8aa3b, v31
	v_exp_f32_e32 v32, v32
	v_exp_f32_e32 v33, v33
	v_add_f32_e32 v3, 1.0, v3
	v_rcp_f32_e32 v38, v3
	v_mul_f32_e32 v3, 0xbfb8aa3b, v37
	v_add_f32_e32 v32, 1.0, v32
	v_add_f32_e32 v33, 1.0, v33
	v_exp_f32_e32 v3, v3
	v_rcp_f32_e32 v32, v32
	v_rcp_f32_e32 v33, v33
	v_cvt_f32_f16_sdwa v27, v9 dst_sel:DWORD dst_unused:UNUSED_PAD src0_sel:WORD_1
	v_add_f32_e32 v3, 1.0, v3
	v_rcp_f32_e32 v39, v3
	v_pk_mul_f32 v[30:31], v[32:33], v[30:31]
	v_cvt_f32_f16_sdwa v33, v7 dst_sel:DWORD dst_unused:UNUSED_PAD src0_sel:WORD_1
	v_cvt_f32_f16_e32 v32, v7
	v_cvt_f32_f16_sdwa v7, v6 dst_sel:DWORD dst_unused:UNUSED_PAD src0_sel:WORD_1
	v_cvt_f32_f16_e32 v6, v6
	v_cvt_f32_f16_sdwa v3, v2 dst_sel:DWORD dst_unused:UNUSED_PAD src0_sel:WORD_1
	v_cvt_f32_f16_e32 v2, v2
	v_cvt_f32_f16_e32 v26, v9
	v_cvt_f32_f16_sdwa v29, v5 dst_sel:DWORD dst_unused:UNUSED_PAD src0_sel:WORD_1
	v_cvt_f32_f16_e32 v28, v5
	v_cvt_f32_f16_sdwa v9, v8 dst_sel:DWORD dst_unused:UNUSED_PAD src0_sel:WORD_1
	v_cvt_f32_f16_e32 v8, v8
	v_cvt_f32_f16_sdwa v5, v4 dst_sel:DWORD dst_unused:UNUSED_PAD src0_sel:WORD_1
	v_cvt_f32_f16_e32 v4, v4
	v_pk_add_f32 v[2:3], v[6:7], v[2:3]
	v_pk_add_f32 v[32:33], v[32:33], v[34:35]
	v_pk_mul_f32 v[6:7], v[2:3], v[2:3]
	v_pk_mul_f32 v[34:35], v[32:33], v[32:33]
	v_add_f32_e32 v6, v6, v7
	v_pk_add_f32 v[4:5], v[8:9], v[4:5]
	v_add_f32_e32 v6, v34, v6
	v_pk_mul_f32 v[8:9], v[4:5], v[4:5]
	v_add_f32_e32 v6, v35, v6
	v_pk_add_f32 v[26:27], v[26:27], v[28:29]
	v_add_f32_e32 v6, v8, v6
	v_pk_mul_f32 v[28:29], v[26:27], v[26:27]
	v_add_f32_e32 v6, v9, v6
	v_add_f32_e32 v6, v28, v6
	v_add_f32_e32 v6, v29, v6
	v_cvt_f32_f16_e32 v22, v104
	v_cvt_f32_f16_sdwa v23, v104 dst_sel:DWORD dst_unused:UNUSED_PAD src0_sel:WORD_1
	v_add_f32_dpp v6, v6, v6 quad_perm:[1,0,3,2] row_mask:0xf bank_mask:0xf bound_ctrl:1
	v_cvt_f32_f16_e32 v24, v105
	v_cvt_f32_f16_sdwa v25, v105 dst_sel:DWORD dst_unused:UNUSED_PAD src0_sel:WORD_1
	v_add_f32_dpp v6, v6, v6 quad_perm:[2,3,0,1] row_mask:0xf bank_mask:0xf bound_ctrl:1
	v_cvt_f32_f16_e32 v18, v102
	v_cvt_f32_f16_sdwa v19, v102 dst_sel:DWORD dst_unused:UNUSED_PAD src0_sel:WORD_1
	v_add_f32_dpp v6, v6, v6 row_half_mirror row_mask:0xf bank_mask:0xf bound_ctrl:1
	v_fmamk_f32 v6, v6, 0x3c800000, v229
	v_rsq_f32_e32 v6, v6
	v_cvt_f32_f16_e32 v20, v103
	v_cvt_f32_f16_sdwa v21, v103 dst_sel:DWORD dst_unused:UNUSED_PAD src0_sel:WORD_1
	v_mul_f32_e32 v22, 0xbfb8aa3b, v22
	v_pk_mul_f32 v[4:5], v[4:5], v[6:7] op_sel_hi:[1,0]
	v_pk_mul_f32 v[8:9], v[32:33], v[6:7] op_sel_hi:[1,0]
	v_pk_mul_f32 v[4:5], v[10:11], v[4:5]
	v_cvt_f32_f16_sdwa v11, v101 dst_sel:DWORD dst_unused:UNUSED_PAD src0_sel:WORD_1
	v_cvt_f32_f16_e32 v10, v101
	v_mul_f32_e32 v23, 0xbfb8aa3b, v23
	v_mul_f32_e32 v24, 0xbfb8aa3b, v24
	v_mul_f32_e32 v25, 0xbfb8aa3b, v25
	v_pk_mul_f32 v[36:37], v[38:39], v[36:37]
	v_cvt_f32_f16_sdwa v39, v98 dst_sel:DWORD dst_unused:UNUSED_PAD src0_sel:WORD_1
	v_cvt_f32_f16_e32 v38, v98
	v_pk_mul_f32 v[2:3], v[2:3], v[6:7] op_sel_hi:[1,0]
	v_pk_mul_f32 v[8:9], v[12:13], v[8:9]
	v_mul_f32_e32 v7, 0xbfb8aa3b, v10
	v_mul_f32_e32 v13, 0xbfb8aa3b, v11
	v_exp_f32_e32 v22, v22
	v_exp_f32_e32 v23, v23
	v_exp_f32_e32 v24, v24
	v_exp_f32_e32 v25, v25
	v_exp_f32_e32 v7, v7
	v_exp_f32_e32 v13, v13
	v_mul_f32_e32 v18, 0xbfb8aa3b, v18
	v_mul_f32_e32 v19, 0xbfb8aa3b, v19
	v_mul_f32_e32 v20, 0xbfb8aa3b, v20
	v_mul_f32_e32 v21, 0xbfb8aa3b, v21
	v_mul_f32_e32 v40, 0xbfb8aa3b, v38
	v_mul_f32_e32 v41, 0xbfb8aa3b, v39
	v_exp_f32_e32 v18, v18
	v_exp_f32_e32 v19, v19
	v_exp_f32_e32 v20, v20
	v_exp_f32_e32 v21, v21
	v_add_f32_e32 v22, 1.0, v22
	v_add_f32_e32 v23, 1.0, v23
	v_add_f32_e32 v24, 1.0, v24
	v_add_f32_e32 v25, 1.0, v25
	v_exp_f32_e32 v40, v40
	v_exp_f32_e32 v41, v41
	v_add_f32_e32 v7, 1.0, v7
	v_add_f32_e32 v13, 1.0, v13
	v_rcp_f32_e32 v22, v22
	v_rcp_f32_e32 v23, v23
	v_rcp_f32_e32 v24, v24
	v_rcp_f32_e32 v25, v25
	v_rcp_f32_e32 v12, v7
	v_rcp_f32_e32 v13, v13
	v_pk_mul_f32 v[6:7], v[26:27], v[6:7] op_sel_hi:[1,0]
	v_add_f32_e32 v18, 1.0, v18
	v_add_f32_e32 v19, 1.0, v19
	v_add_f32_e32 v20, 1.0, v20
	v_add_f32_e32 v21, 1.0, v21
	v_add_f32_e32 v40, 1.0, v40
	v_add_f32_e32 v41, 1.0, v41
	v_pk_mul_f32 v[6:7], v[16:17], v[6:7]
	v_rcp_f32_e32 v18, v18
	v_rcp_f32_e32 v19, v19
	v_rcp_f32_e32 v20, v20
	v_rcp_f32_e32 v21, v21
	v_rcp_f32_e32 v40, v40
	v_rcp_f32_e32 v41, v41
	v_pk_mul_f32 v[4:5], v[22:23], v[4:5]
	v_pk_mul_f32 v[6:7], v[24:25], v[6:7]
	v_pk_mul_f32 v[10:11], v[12:13], v[10:11]
	v_pk_mul_f32 v[4:5], v[30:31], v[4:5]
	v_pk_mul_f32 v[6:7], v[10:11], v[6:7]
	v_cvt_pk_f16_f32 v4, v4, v5
	v_cvt_pk_f16_f32 v5, v6, v7
	v_lshl_add_u64 v[6:7], s[16:17], 0, v[156:157]
	v_pk_mul_f32 v[2:3], v[14:15], v[2:3]
	v_lshlrev_b64 v[6:7], 11, v[6:7]
	v_pk_mul_f32 v[38:39], v[40:41], v[38:39]
	v_pk_mul_f32 v[2:3], v[18:19], v[2:3]
	v_pk_mul_f32 v[8:9], v[20:21], v[8:9]
	v_lshl_add_u64 v[6:7], s[44:45], 0, v[6:7]
	v_pk_mul_f32 v[2:3], v[38:39], v[2:3]
	v_pk_mul_f32 v[8:9], v[36:37], v[8:9]
	v_lshl_add_u64 v[6:7], v[6:7], 0, s[20:21]
	v_cvt_pk_f16_f32 v2, v2, v3
	v_cvt_pk_f16_f32 v3, v8, v9
	v_lshl_add_u64 v[6:7], v[6:7], 0, v[0:1]
	global_store_dwordx4 v[6:7], v[2:5], off offset:1536
	s_waitcnt lgkmcnt(0)
	s_barrier
	s_mov_b64 s[16:17], -1
	s_nop 0
	v_mov_b32_e32 v3, v215
	s_cbranch_vccnz .LBB0_436

; #define LAS __attribute__((address_space(3)))
; #define GAS __attribute__((address_space(1)))
; #define BAR_LDS() asm volatile("s_waitcnt lgkmcnt(0)\n\ts_barrier" ::: "memory")
; __device__ __forceinline__ void mlstm_out_loop(unsigned char* ws, h16* Y, const float* ghead  , int u  , const int o_mout, const int o_end, const int ntc, const bool ctx_out, ...
;     ...
;         for (int j = 0; j < 2; ++j) { const int i = tid + 512 * j, row = i >> 3, c8 = i & 7, sl = row >> 6, r = row & 63;
;             *(LAS u32x4*)(lds + MO_K + sl * 8192 + c8 * 1024 + r * 16) = R.kv[j];
;             *(LAS u32x4*)(lds + MO_V + sl * 8192 + ((c8 >> 2) * 4 + (r >> 4)) * 1024 + (r & 15) * 64 + (c8 & 3) * 16) = R.vv[j];
;             *(LAS u32x4*)(lds + MO_Q + c8 * 2048 + row * 16) = R.qv[j]; }
; #pragma unroll
;         for (int d = 0; d < 2; ++d) *(LAS u32x4*)(lds + MO_CF + d * 8192 + (tid & 7) * 1024 + (tid >> 3) * 16) = R.cfv[d];
;         LAS float* bL = (LAS float*)(lds + MO_GA + dir * 1536); LAS float* gL = bL + 128; LAS float* ML = bL + 256; LAS float* NL = (LAS float*)(lds + MO_N + dir * 256); LAS float* M0 = (LAS float*)(lds + MO_M0);
;         if (wl == 0) { float Gm, be; gate_compute(R.graw, dir, m0g, bL, gL, ML, lane, Gm, be); NL[lane] = nval; if (lane == 0) M0[dir] = m0g; }
;         if (tid == 0) *slot = (int)nxt;
;         BAR_LDS();
;         const int un = __builtin_amdgcn_readfirstlane(*slot); const bool more = un < o_end;
;         int nb = 0, nh = 0, ntcv = 0;
;         if (more) { const int a = un - o_mout, tci = a % ntc, bh = a / ntc; nb = bh >> 2; nh = bh & 3; ntcv = ctx_out ? tci : tci + 2; mout_load(R, ws, nb, nh, ntcv, tid); mout_load_mn(R, ws, nb, nh, ntcv, tid); }
;         const int frow = tid >> 3, fc8 = tid & 7; const size_t fgo = (rb + frow) * 256 + h * 64 + fc8 * 8;
;         const h16x8 co0 = *(const GAS h16x8*)((const h16*)(ws + WS_CO) + fgo), co1 = *(const GAS h16x8*)((const h16*)(ws + WS_CO) + fgo + 64 * 256), cz0 = *(const GAS h16x8*)((const h16*)(ws + WS_CZ) + fgo), cz1 = *(const GAS h16x8*)((const h16*)(ws + WS_CZ) + fgo + 64 * 256);
.LBB0_414:
	s_waitcnt vmcnt(5)
	ds_write_b128 v183, v[66:69]
	s_waitcnt vmcnt(4)
	ds_write_b128 v184, v[70:73] offset:16384
	s_waitcnt vmcnt(3)
	ds_write_b128 v185, v[74:77]
	s_waitcnt vmcnt(2)
	ds_write_b128 v186, v[78:81]
	s_waitcnt vmcnt(1)
	ds_write_b128 v187, v[82:85] offset:16384
	s_waitcnt vmcnt(0)
	ds_write_b128 v188, v[86:89]
	ds_write_b128 v189, v[90:93]
	ds_write_b128 v189, v[94:97] offset:8192
	v_lshl_add_u64 v[158:159], s[16:17], 0, v[138:139]
	s_lshl_b32 vcc_lo, s76, 6
	s_mov_b32 vcc_hi, 0
	v_lshlrev_b64 v[98:99], 8, v[158:159]
	s_nop 1
	v_lshl_add_u64 v[98:99], v[98:99], 0, vcc
	v_or_b32_e32 v98, v98, v136
	v_lshlrev_b64 v[98:99], 1, v[98:99]
	v_lshl_add_u64 v[100:101], s[8:9], 0, v[98:99]
	v_add_co_u32_e32 v102, vcc, 0x8000, v100
	v_lshl_add_u64 v[98:99], s[18:19], 0, v[98:99]
	s_nop 0
	v_addc_co_u32_e32 v103, vcc, 0, v101, vcc
	global_load_dwordx4 v[110:113], v[100:101], off
	global_load_dwordx4 v[102:105], v[102:103], off
	v_add_co_u32_e32 v100, vcc, 0x8000, v98
	s_nop 1
	v_addc_co_u32_e32 v101, vcc, 0, v99, vcc
	global_load_dwordx4 v[106:109], v[98:99], off
	global_load_dwordx4 v[98:101], v[100:101], off
	s_andn2_b64 vcc, exec, s[10:11]
	s_cbranch_vccz .LBB0_433
	s_and_saveexec_b64 s[0:1], s[38:39]

; #define LAS __attribute__((address_space(3)))
; __device__ __forceinline__ void mlstm_out_loop(unsigned char* ws, h16* Y, const float* ghead  , int u  , const int o_mout, const int o_end, const int ntc, const bool ctx_out, ...
;     ...
;         s16x8 qr[4], cf[4][2];
; #pragma unroll
;         for (int d0 = 0; d0 < 4; ++d0) qr[d0] = *(const LAS s16x8*)(lds + MO_Q + (2 * d0 + hi) * 2048 + (32 * wl + r32) * 16);
; #pragma unroll
;         for (int ks = 0; ks < 4; ++ks)
; #pragma unroll
;             for (int d0 = 0; d0 < 2; ++d0) cf[ks][d0] = *(const LAS s16x8*)(lds + MO_CF + dir * 8192 + (2 * ks + hi) * 1024 + (32 * d0 + r32) * 16);
;         const int t = 32 * wl + r32;
;         const float m0 = M0[dir], Mt = ML[t], bt = bL[t], inter = __builtin_amdgcn_exp2f((m0 - Mt) * LOG2E);
;         f32x16 o[2]; o[0] = f32x16{}; o[1] = f32x16{}; float sacc = 0.f; const f32x16 zero16 = f32x16{};
;         const unsigned lds0 = (unsigned)(uintptr_t)shm;
;         { float dq = 0.f; const h16 ih = (h16)inter;
; #pragma unroll
;           for (int ks = 0; ks < 4; ++ks) { const h16x8 q8 = H8(qr[ks]); const f32x4 n0 = *(const LAS f32x4*)(NL + 16 * ks + 8 * hi), n1 = *(const LAS f32x4*)(NL + 16 * ks + 8 * hi + 4);
;               dq += ((float)q8[0] * n0[0] + (float)q8[1] * n0[1]) + ((float)q8[2] * n0[2] + (float)q8[3] * n0[3]) + ((float)q8[4] * n1[0] + (float)q8[5] * n1[1]) + ((float)q8[6] * n1[2] + (float)q8[7] * n1[3]);
;               const h16x8 qs = q8 * ih;
; #pragma unroll
;               for (int d0 = 0; d0 < 2; ++d0) o[d0] = __builtin_amdgcn_mfma_f32_32x32x16_f16(qs, H8(cf[ks][d0]), o[d0], 0, 0, 0); }
;           sacc += inter * dq; }
.LBB0_427:
	s_lshl_b32 s20, s76, 6
	s_mov_b32 s21, s40
	s_add_i32 s0, s83, s84
	s_nop 0
	v_mov_b32_e32 v2, s0
	ds_read_b128 v[126:129], v190
	ds_read_b128 v[122:125], v190 offset:4096
	ds_read_b128 v[118:121], v190 offset:8192
	ds_read_b128 v[114:117], v190 offset:12288
	ds_read_b32 v10, v2 offset:37376
	ds_read2st64_b32 v[160:161], v175 offset0:128 offset1:132
	ds_read_b128 v[2:5], v191
	ds_read_b128 v[18:21], v191 offset:512
	ds_read_b128 v[38:41], v191 offset:2048
	ds_read_b128 v[42:45], v191 offset:2560
	ds_read_b128 v[6:9], v192 offset:36864
	s_waitcnt lgkmcnt(5)
	v_sub_f32_e32 v10, v10, v161
	v_mul_f32_e32 v10, 0x3fb8aa3b, v10
	v_exp_f32_e32 v210, v10
	ds_read_b128 v[46:49], v191 offset:4096
	ds_read_b128 v[50:53], v191 offset:4608
	ds_read_b128 v[54:57], v191 offset:6144
	ds_read_b128 v[34:37], v191 offset:6656
	ds_read_b128 v[22:25], v192 offset:36880
	ds_read_b128 v[58:61], v192 offset:36928
	v_cvt_f16_f32_e32 v211, v210
	v_cvt_f32_f16_e32 v12, v126
	v_cvt_f32_f16_sdwa v13, v127 dst_sel:DWORD dst_unused:UNUSED_PAD src0_sel:WORD_1
	v_cvt_f32_f16_e32 v11, v127
	v_cvt_f32_f16_sdwa v10, v126 dst_sel:DWORD dst_unused:UNUSED_PAD src0_sel:WORD_1
	v_pk_mul_f16 v29, v129, v211 op_sel_hi:[1,0]
	v_pk_mul_f16 v28, v128, v211 op_sel_hi:[1,0]
	v_pk_mul_f16 v27, v127, v211 op_sel_hi:[1,0]
	v_pk_mul_f16 v26, v126, v211 op_sel_hi:[1,0]
	v_cvt_f32_f16_sdwa v65, v128 dst_sel:DWORD dst_unused:UNUSED_PAD src0_sel:WORD_1
	v_cvt_f32_f16_sdwa v64, v129 dst_sel:DWORD dst_unused:UNUSED_PAD src0_sel:WORD_1
	v_cvt_f32_f16_e32 v33, v128
	v_cvt_f32_f16_e32 v32, v129
	s_waitcnt lgkmcnt(6)
	v_mov_b32_e32 v14, v7
	v_mov_b32_e32 v7, v9
	v_mov_b32_e32 v15, v8
	v_pk_mul_f32 v[6:7], v[6:7], v[12:13]
	s_waitcnt lgkmcnt(1)
	v_mov_b32_e32 v63, v22
	v_mov_b32_e32 v22, v25
	v_pk_fma_f32 v[30:31], v[14:15], v[10:11], v[6:7]
	v_mov_b32_e32 v62, v24
	v_pk_mul_f32 v[22:23], v[22:23], v[64:65]
	v_mfma_f32_32x32x16_f16 v[2:17], v[26:29], v[2:5], 0
	v_fma_f32 v22, v62, v32, v22
	v_fma_f32 v23, v63, v33, v23
	v_add_f32_e32 v24, v30, v31
	v_add_f32_e32 v23, v24, v23
	v_add_f32_e32 v62, v22, v23
	v_add_f32_e32 v132, 0, v62
	v_pk_mul_f16 v65, v125, v211 op_sel_hi:[1,0]
	v_pk_mul_f16 v64, v124, v211 op_sel_hi:[1,0]
	v_mfma_f32_32x32x16_f16 v[18:33], v[26:29], v[18:21], 0
	v_pk_mul_f16 v63, v123, v211 op_sel_hi:[1,0]
	v_pk_mul_f16 v62, v122, v211 op_sel_hi:[1,0]
	v_cvt_f32_f16_e32 v220, v122
	v_cvt_f32_f16_sdwa v221, v123 dst_sel:DWORD dst_unused:UNUSED_PAD src0_sel:WORD_1
	v_cvt_f32_f16_e32 v135, v123
	v_cvt_f32_f16_sdwa v134, v122 dst_sel:DWORD dst_unused:UNUSED_PAD src0_sel:WORD_1
	s_waitcnt lgkmcnt(0)
	v_mov_b32_e32 v218, v59
	v_mov_b32_e32 v59, v61
	v_mov_b32_e32 v219, v60
	v_mfma_f32_32x32x16_f16 v[2:17], v[62:65], v[38:41], v[2:17]
	v_mul_f32_e64 v38, v58, v220
	v_mul_f32_e64 v39, v59, v221
	v_cvt_f32_f16_sdwa v221, v124 dst_sel:DWORD dst_unused:UNUSED_PAD src0_sel:WORD_1
	v_fma_f32 v38, v218, v134, v38
	v_fma_f32 v39, v219, v135, v39
	v_cvt_f32_f16_sdwa v220, v125 dst_sel:DWORD dst_unused:UNUSED_PAD src0_sel:WORD_1
	v_pk_add_f32 v[134:135], v[38:39], v[38:39] op_sel:[0,1] op_sel_hi:[1,0]
	v_cvt_f32_f16_e32 v219, v124
	v_cvt_f32_f16_e32 v218, v125
	v_mfma_f32_32x32x16_f16 v[18:33], v[62:65], v[42:45], v[18:33]
	ds_read_b128 v[38:41], v192 offset:36944
	ds_read_b128 v[42:45], v192 offset:36992
	v_pk_mul_f16 v61, v121, v211 op_sel_hi:[1,0]
	v_pk_mul_f16 v60, v120, v211 op_sel_hi:[1,0]
	v_pk_mul_f16 v59, v119, v211 op_sel_hi:[1,0]
	v_pk_mul_f16 v58, v118, v211 op_sel_hi:[1,0]
	s_waitcnt lgkmcnt(1)
	v_mov_b32_e32 v63, v38
	v_mov_b32_e32 v38, v41
	v_mov_b32_e32 v62, v40
	v_pk_mul_f32 v[38:39], v[38:39], v[220:221]
	v_mfma_f32_32x32x16_f16 v[2:17], v[58:61], v[46:49], v[2:17]
	v_fma_f32 v38, v62, v218, v38
	v_fma_f32 v39, v63, v219, v39
	v_cvt_f32_f16_sdwa v65, v118 dst_sel:DWORD dst_unused:UNUSED_PAD src0_sel:WORD_1
	v_add_f32_e64 v40, v134, v39
	v_add_f32_e64 v41, v135, v38
	v_cvt_f32_f16_e32 v64, v118
	v_pk_add_f32 v[62:63], v[38:39], v[40:41]
	v_cvt_f32_f16_sdwa v135, v119 dst_sel:DWORD dst_unused:UNUSED_PAD src0_sel:WORD_1
	v_cvt_f32_f16_e32 v134, v119
	v_mfma_f32_32x32x16_f16 v[18:33], v[58:61], v[50:53], v[18:33]
	ds_read_b128 v[38:41], v192 offset:37008
	ds_read_b128 v[46:49], v192 offset:37056
	ds_read_b128 v[50:53], v192 offset:37072
	v_cvt_f32_f16_e32 v60, v117
	v_cvt_f32_f16_sdwa v61, v117 dst_sel:DWORD dst_unused:UNUSED_PAD src0_sel:WORD_1
	v_cvt_f32_f16_sdwa v59, v115 dst_sel:DWORD dst_unused:UNUSED_PAD src0_sel:WORD_1
	v_cvt_f32_f16_e32 v58, v115
	s_waitcnt lgkmcnt(0)
	v_mul_f32_e32 v133, v52, v60
	v_mul_f32_e32 v63, v53, v61
	v_cvt_f32_f16_sdwa v53, v114 dst_sel:DWORD dst_unused:UNUSED_PAD src0_sel:WORD_1
	v_cvt_f32_f16_sdwa v52, v120 dst_sel:DWORD dst_unused:UNUSED_PAD src0_sel:WORD_1
	v_mul_f32_e32 v219, v49, v59
	v_mov_b32_e32 v59, v46
	v_mov_b32_e32 v46, v39
	v_mul_f32_e32 v218, v48, v58
	v_cvt_f32_f16_e32 v49, v114
	v_cvt_f32_f16_e32 v48, v120
	v_mov_b32_e32 v58, v38
	v_pk_mul_f32 v[38:39], v[46:47], v[52:53]
	v_mul_f32_e32 v46, v43, v65
	v_pk_fma_f32 v[42:43], v[42:43], v[64:65], v[46:47] op_sel_hi:[1,1,0]
	v_mul_f32_e32 v46, v45, v135
	v_pk_fma_f32 v[44:45], v[44:45], v[134:135], v[46:47] op_sel_hi:[1,1,0]
	v_mov_b32_e32 v43, v218
	v_mov_b32_e32 v45, v219
	v_pk_fma_f32 v[38:39], v[58:59], v[48:49], v[38:39]
	v_pk_add_f32 v[42:43], v[42:43], v[44:45]
	v_pk_mul_f16 v45, v117, v211 op_sel_hi:[1,0]
	v_pk_add_f32 v[38:39], v[38:39], v[42:43]
	v_pk_mul_f16 v44, v116, v211 op_sel_hi:[1,0]
	v_pk_mul_f16 v43, v115, v211 op_sel_hi:[1,0]
	v_pk_mul_f16 v42, v114, v211 op_sel_hi:[1,0]
	v_cvt_f32_f16_sdwa v53, v116 dst_sel:DWORD dst_unused:UNUSED_PAD src0_sel:WORD_1
	v_cvt_f32_f16_sdwa v52, v121 dst_sel:DWORD dst_unused:UNUSED_PAD src0_sel:WORD_1
	v_cvt_f32_f16_e32 v47, v116
	v_cvt_f32_f16_e32 v46, v121
	v_mfma_f32_32x32x16_f16 v[2:17], v[42:45], v[54:57], v[2:17]
	v_mov_b32_e32 v49, v50
	v_mov_b32_e32 v50, v41
	v_mov_b32_e32 v48, v40
	v_mul_f32_e64 v40, v50, v52
	v_mul_f32_e64 v41, v51, v53
	s_andn2_b64 vcc, exec, s[12:13]
	v_pk_fma_f32 v[40:41], v[48:49], v[46:47], v[40:41]
	v_mfma_f32_32x32x16_f16 v[18:33], v[42:45], v[34:37], v[18:33]
	v_add_f32_e64 v38, v38, v40
	v_add_f32_e64 v39, v39, v41
	v_add_f32_e64 v40, v132, v62
	v_add_f32_e64 v41, v133, v63
	v_add_f32_e64 v38, v40, v38
	v_add_f32_e64 v39, v41, v39
	v_add_f32_e32 v34, v38, v39
	v_fma_f32 v222, v210, v34, 0
	s_cbranch_vccnz .LBB0_429
; #define LAS __attribute__((address_space(3)))
; __device__ __forceinline__ void mlstm_out_loop(unsigned char* ws, h16* Y, const float* ghead  , int u  , const int o_mout, const int o_end, const int ntc, const bool ctx_out, ...
;     ...
;         for (int kb = 0; kb < 2; ++kb) {
;             const bool need = dir ? (kb == 1 || wl <= 1) : (kb == 0 || wl >= 2);
;             if (need) {
;                 f32x16 p0, p1; attn_body::qkt(p0, p1, shm + MO_K + kb * 8192, qr, zero16, r32, hi);
; #pragma unroll
;                 for (int i = 0; i < 4; ++i) { const f32x4 ga = *(const LAS f32x4*)(gL + 64 * kb + 8 * i + 4 * hi), gb = *(const LAS f32x4*)(gL + 64 * kb + 32 + 8 * i + 4 * hi);
; #pragma unroll
;                     for (int jj = 0; jj < 4; ++jj) { const int r = 4 * i + jj, s0 = 64 * kb + 8 * i + 4 * hi + jj, s1 = s0 + 32;
;                         const bool k0 = dir ? (s0 >= t) : (s0 <= t), k1 = dir ? (s1 >= t) : (s1 <= t);
;                         const float w0 = k0 ? p0[r] * __builtin_amdgcn_exp2f((ga[jj] - Mt) * LOG2E) : 0.f, w1 = k1 ? p1[r] * __builtin_amdgcn_exp2f((gb[jj] - Mt) * LOG2E) : 0.f;
;                         p0[r] = w0; p1[r] = w1; sacc += w0 + w1; } }
	ds_read_b128 v[34:37], v214 offset:512
	ds_read_b128 v[38:41], v214
	ds_read_b128 v[132:135], v214 offset:2560
	ds_read_b128 v[218:221], v214 offset:2048
	v_readlane_b32 s0, v253, 14
	v_readlane_b32 s1, v253, 15
	s_waitcnt lgkmcnt(2)
	v_mfma_f32_32x32x16_f16 v[50:65], v[38:41], v[126:129], 0
	v_mfma_f32_32x32x16_f16 v[34:49], v[34:37], v[126:129], 0
	s_waitcnt lgkmcnt(0)
	v_mfma_f32_32x32x16_f16 v[50:65], v[218:221], v[122:125], v[50:65]
	v_mfma_f32_32x32x16_f16 v[34:49], v[132:135], v[122:125], v[34:49]
	ds_read_b128 v[132:135], v214 offset:4608
	ds_read_b128 v[218:221], v214 offset:4096
	s_waitcnt lgkmcnt(0)
	v_mfma_f32_32x32x16_f16 v[50:65], v[218:221], v[118:121], v[50:65]
	v_mfma_f32_32x32x16_f16 v[34:49], v[132:135], v[118:121], v[34:49]
	ds_read_b128 v[132:135], v214 offset:6656
	ds_read_b128 v[218:221], v214 offset:6144
	s_waitcnt lgkmcnt(0)
	v_mfma_f32_32x32x16_f16 v[50:65], v[218:221], v[114:117], v[50:65]
	v_mfma_f32_32x32x16_f16 v[34:49], v[132:135], v[114:117], v[34:49]
	ds_read_b128 v[224:227], v178 offset:33408
	ds_read_b128 v[218:221], v178 offset:33280
	ds_read_b128 v[132:135], v178 offset:33312
	s_waitcnt lgkmcnt(1)
	v_sub_f32_e32 v210, v218, v161
	v_mul_f32_e32 v210, 0x3fb8aa3b, v210
	v_exp_f32_e32 v210, v210
	s_waitcnt lgkmcnt(0)
	v_sub_f32_e32 v132, v132, v161
	v_mul_f32_e32 v132, 0x3fb8aa3b, v132
	v_exp_f32_e32 v132, v132
	v_mul_f32_e32 v50, v50, v210
	v_cndmask_b32_e64 v218, 0, v50, s[0:1]
	v_sub_f32_e32 v50, v224, v161
	v_mul_f32_e32 v50, 0x3fb8aa3b, v50
	v_exp_f32_e32 v50, v50
	v_sub_f32_e32 v210, v219, v161
	v_mul_f32_e32 v210, 0x3fb8aa3b, v210
	v_exp_f32_e32 v210, v210
	v_readlane_b32 s0, v253, 16
	v_mul_f32_e32 v34, v34, v50
	v_readlane_b32 s1, v253, 17
	v_mul_f32_e32 v51, v51, v210
	v_mul_f32_e32 v54, v54, v132
	v_cndmask_b32_e64 v50, 0, v34, s[0:1]
	v_readlane_b32 s0, v253, 18
	v_readlane_b32 s1, v253, 19
	v_add_f32_e32 v34, v218, v50
	v_add_f32_e32 v34, v222, v34
	v_cndmask_b32_e64 v219, 0, v51, s[0:1]
	v_sub_f32_e32 v51, v225, v161
	v_mul_f32_e32 v51, 0x3fb8aa3b, v51
	v_exp_f32_e32 v51, v51
	v_readlane_b32 s0, v253, 20
	v_readlane_b32 s1, v253, 21
	v_mul_f32_e32 v35, v35, v51
	s_nop 0
	v_cndmask_b32_e64 v51, 0, v35, s[0:1]
	v_add_f32_e32 v35, v219, v51
	v_add_f32_e32 v34, v35, v34
	v_sub_f32_e32 v35, v220, v161
	v_mul_f32_e32 v35, 0x3fb8aa3b, v35
	v_exp_f32_e32 v35, v35
	v_readlane_b32 s0, v253, 22
	v_readlane_b32 s1, v253, 23
	v_mul_f32_e32 v35, v52, v35
	s_nop 0
	v_cndmask_b32_e64 v220, 0, v35, s[0:1]
	v_sub_f32_e32 v35, v226, v161
	v_mul_f32_e32 v35, 0x3fb8aa3b, v35
	v_exp_f32_e32 v35, v35
	v_readlane_b32 s0, v253, 10
	v_readlane_b32 s1, v253, 11
	v_mul_f32_e32 v35, v36, v35
	s_nop 0
	v_cndmask_b32_e64 v52, 0, v35, s[0:1]
	v_add_f32_e32 v35, v220, v52
	v_add_f32_e32 v34, v35, v34
	v_sub_f32_e32 v35, v221, v161
	v_mul_f32_e32 v35, 0x3fb8aa3b, v35
	v_exp_f32_e32 v35, v35
	v_readlane_b32 s0, v253, 28
	v_readlane_b32 s1, v253, 29
	v_mul_f32_e32 v35, v53, v35
	s_nop 0
	v_cndmask_b32_e64 v221, 0, v35, s[0:1]
	v_sub_f32_e32 v35, v227, v161
	v_mul_f32_e32 v35, 0x3fb8aa3b, v35
	v_exp_f32_e32 v35, v35
	v_readlane_b32 s0, v253, 30
	v_readlane_b32 s1, v253, 31
	v_mul_f32_e32 v35, v37, v35
	s_nop 0
	v_cndmask_b32_e64 v53, 0, v35, s[0:1]
	v_add_f32_e32 v35, v221, v53
	v_add_f32_e32 v210, v35, v34
	ds_read_b128 v[34:37], v178 offset:33440
	v_readlane_b32 s0, v253, 32
	v_readlane_b32 s1, v253, 33
	s_waitcnt lgkmcnt(0)
	v_sub_f32_e32 v34, v34, v161
	v_mul_f32_e32 v34, 0x3fb8aa3b, v34
	v_exp_f32_e32 v34, v34
	v_sub_f32_e32 v35, v35, v161
	v_cndmask_b32_e64 v54, 0, v54, s[0:1]
	v_readlane_b32 s0, v253, 34
	v_mul_f32_e32 v34, v38, v34
	v_sub_f32_e32 v38, v133, v161
	v_mul_f32_e32 v38, 0x3fb8aa3b, v38
	v_exp_f32_e32 v38, v38
	v_mul_f32_e32 v35, 0x3fb8aa3b, v35
	v_readlane_b32 s1, v253, 35
	v_exp_f32_e32 v35, v35
	v_mul_f32_e32 v38, v55, v38
	v_cndmask_b32_e64 v132, 0, v34, s[0:1]
	v_readlane_b32 s0, v253, 36
	v_readlane_b32 s1, v253, 37
	v_mul_f32_e32 v35, v39, v35
	v_add_f32_e32 v34, v54, v132
	v_cndmask_b32_e64 v55, 0, v38, s[0:1]
	v_readlane_b32 s0, v253, 38
	v_readlane_b32 s1, v253, 39
	v_add_f32_e32 v34, v34, v210
	s_nop 0
	v_cndmask_b32_e64 v133, 0, v35, s[0:1]
	v_add_f32_e32 v35, v55, v133
	v_add_f32_e32 v34, v35, v34
	v_sub_f32_e32 v35, v134, v161
	v_mul_f32_e32 v35, 0x3fb8aa3b, v35
	v_exp_f32_e32 v35, v35
	v_readlane_b32 s0, v253, 40
	v_readlane_b32 s1, v253, 41
	v_mul_f32_e32 v35, v56, v35
	s_nop 0
	v_cndmask_b32_e64 v56, 0, v35, s[0:1]
	v_sub_f32_e32 v35, v36, v161
	v_mul_f32_e32 v35, 0x3fb8aa3b, v35
	v_exp_f32_e32 v35, v35
	v_readlane_b32 s0, v253, 42
	v_readlane_b32 s1, v253, 43
	v_mul_f32_e32 v35, v40, v35
	s_nop 0
	v_cndmask_b32_e64 v134, 0, v35, s[0:1]
	v_add_f32_e32 v35, v56, v134
	v_add_f32_e32 v34, v35, v34
	v_sub_f32_e32 v35, v135, v161
	v_mul_f32_e32 v35, 0x3fb8aa3b, v35
	v_exp_f32_e32 v35, v35
	v_readlane_b32 s0, v253, 44
	v_readlane_b32 s1, v253, 45
	v_mul_f32_e32 v35, v57, v35
	s_nop 0
	v_cndmask_b32_e64 v57, 0, v35, s[0:1]
	v_sub_f32_e32 v35, v37, v161
	v_mul_f32_e32 v35, 0x3fb8aa3b, v35
	v_exp_f32_e32 v35, v35
	v_readlane_b32 s0, v253, 46
	v_readlane_b32 s1, v253, 47
	v_mul_f32_e32 v35, v41, v35
	s_nop 0
	v_cndmask_b32_e64 v135, 0, v35, s[0:1]
	v_add_f32_e32 v35, v57, v135
	v_add_f32_e32 v210, v35, v34
	ds_read_b128 v[34:37], v178 offset:33344
	ds_read_b128 v[38:41], v178 offset:33472
	v_readlane_b32 s0, v253, 48
	v_readlane_b32 s1, v253, 49
	s_waitcnt lgkmcnt(1)
	v_sub_f32_e32 v34, v34, v161
	v_mul_f32_e32 v34, 0x3fb8aa3b, v34
	v_exp_f32_e32 v34, v34
	v_sub_f32_e32 v35, v35, v161
	v_mul_f32_e32 v35, 0x3fb8aa3b, v35
	v_exp_f32_e32 v35, v35
	v_mul_f32_e32 v34, v58, v34
	v_cndmask_b32_e64 v58, 0, v34, s[0:1]
	s_waitcnt lgkmcnt(0)
; #define LAS __attribute__((address_space(3)))
; #define PKW(P, B) cvtpk_h(P[B], P[B + 1])
; #define PKW(P, B) cvtpk_h(P[B], P[B + 1])
; __device__ __forceinline__ void mlstm_out_loop(unsigned char* ws, h16* Y, const float* ghead  , int u  , const int o_mout, const int o_end, const int ntc, const bool ctx_out, ...
;     ...
;                 for (int i = 0; i < 4; ++i) { const f32x4 ga = *(const LAS f32x4*)(gL + 64 * kb + 8 * i + 4 * hi), gb = *(const LAS f32x4*)(gL + 64 * kb + 32 + 8 * i + 4 * hi);
; #pragma unroll
;                     for (int jj = 0; jj < 4; ++jj) { const int r = 4 * i + jj, s0 = 64 * kb + 8 * i + 4 * hi + jj, s1 = s0 + 32;
;                         const bool k0 = dir ? (s0 >= t) : (s0 <= t), k1 = dir ? (s1 >= t) : (s1 <= t);
;                         const float w0 = k0 ? p0[r] * __builtin_amdgcn_exp2f((ga[jj] - Mt) * LOG2E) : 0.f, w1 = k1 ? p1[r] * __builtin_amdgcn_exp2f((gb[jj] - Mt) * LOG2E) : 0.f;
;                         p0[r] = w0; p1[r] = w1; sacc += w0 + w1; } }
;                 u32x4 pw0, pw1, pw2, pw3;
;     ...
;                 pw0 = (u32x4){PKW(p0, 0), PKW(p0, 2), PKW(p0, 4), PKW(p0, 6)}; pw1 = (u32x4){PKW(p0, 8), PKW(p0, 10), PKW(p0, 12), PKW(p0, 14)};
;                 pw2 = (u32x4){PKW(p1, 0), PKW(p1, 2), PKW(p1, 4), PKW(p1, 6)}; pw3 = (u32x4){PKW(p1, 8), PKW(p1, 10), PKW(p1, 12), PKW(p1, 14)};
;     ...
;                 const int vb = (int)(lds0 + MO_V + kb * 8192) + ((lane >> 4) & 1) * 32 + (lane & 3) * 8 + (4 * hi + ((lane & 15) >> 2)) * 64;
;                 attn_body::pv(o, vb, __builtin_bit_cast(s16x8, pw0), __builtin_bit_cast(s16x8, pw1), __builtin_bit_cast(s16x8, pw2), __builtin_bit_cast(s16x8, pw3));
	v_sub_f32_e32 v34, v38, v161
	v_mul_f32_e32 v34, 0x3fb8aa3b, v34
	v_exp_f32_e32 v34, v34
	v_readlane_b32 s0, v253, 50
	v_readlane_b32 s1, v253, 51
	v_mul_f32_e32 v35, v59, v35
	v_mul_f32_e32 v34, v42, v34
	v_cndmask_b32_e64 v42, 0, v34, s[0:1]
	v_readlane_b32 s0, v253, 52
	v_readlane_b32 s1, v253, 53
	v_add_f32_e32 v34, v58, v42
	v_add_f32_e32 v34, v34, v210
	v_cndmask_b32_e64 v59, 0, v35, s[0:1]
	v_sub_f32_e32 v35, v39, v161
	v_mul_f32_e32 v35, 0x3fb8aa3b, v35
	v_exp_f32_e32 v35, v35
	v_readlane_b32 s0, v253, 54
	v_readlane_b32 s1, v253, 55
	v_mul_f32_e32 v35, v43, v35
	s_nop 0
	v_cndmask_b32_e64 v43, 0, v35, s[0:1]
	v_add_f32_e32 v35, v59, v43
	v_add_f32_e32 v34, v35, v34
	v_sub_f32_e32 v35, v36, v161
	v_mul_f32_e32 v35, 0x3fb8aa3b, v35
	v_exp_f32_e32 v35, v35
	v_readlane_b32 s0, v253, 56
	v_readlane_b32 s1, v253, 57
	v_cvt_pk_f16_f32 v42, v42, v43
	v_mul_f32_e32 v35, v60, v35
	v_cndmask_b32_e64 v60, 0, v35, s[0:1]
	v_sub_f32_e32 v35, v40, v161
	v_mul_f32_e32 v35, 0x3fb8aa3b, v35
	v_exp_f32_e32 v35, v35
	v_readlane_b32 s0, v253, 58
	v_readlane_b32 s1, v253, 59
	v_mul_f32_e32 v35, v44, v35
	s_nop 0
	v_cndmask_b32_e64 v44, 0, v35, s[0:1]
	v_add_f32_e32 v35, v60, v44
	v_add_f32_e32 v34, v35, v34
	v_sub_f32_e32 v35, v37, v161
	v_mul_f32_e32 v35, 0x3fb8aa3b, v35
	v_exp_f32_e32 v35, v35
	v_readlane_b32 s0, v253, 60
	v_readlane_b32 s1, v253, 61
	v_mul_f32_e32 v35, v61, v35
	s_nop 0
	v_cndmask_b32_e64 v61, 0, v35, s[0:1]
	v_sub_f32_e32 v35, v41, v161
	v_mul_f32_e32 v35, 0x3fb8aa3b, v35
	v_exp_f32_e32 v35, v35
	v_readlane_b32 s0, v253, 62
	v_readlane_b32 s1, v253, 63
	v_mul_f32_e32 v35, v45, v35
	s_nop 0
	v_cndmask_b32_e64 v45, 0, v35, s[0:1]
	v_add_f32_e32 v35, v61, v45
	v_add_f32_e32 v210, v35, v34
	ds_read_b128 v[38:41], v178 offset:33376
	ds_read_b128 v[34:37], v178 offset:33504
	v_readlane_b32 s0, v254, 0
	v_readlane_b32 s1, v254, 1
	v_cvt_pk_f16_f32 v43, v44, v45
	s_waitcnt lgkmcnt(1)
	v_sub_f32_e32 v38, v38, v161
	v_mul_f32_e32 v38, 0x3fb8aa3b, v38
	v_exp_f32_e32 v38, v38
	s_waitcnt lgkmcnt(0)
	v_sub_f32_e32 v34, v34, v161
	v_mul_f32_e32 v34, 0x3fb8aa3b, v34
	v_exp_f32_e32 v34, v34
	v_mul_f32_e32 v38, v62, v38
	v_cndmask_b32_e64 v62, 0, v38, s[0:1]
	v_sub_f32_e32 v38, v39, v161
	v_mul_f32_e32 v38, 0x3fb8aa3b, v38
	v_exp_f32_e32 v38, v38
	v_sub_f32_e32 v35, v35, v161
	v_readlane_b32 s0, v254, 2
	v_mul_f32_e32 v35, 0x3fb8aa3b, v35
	v_mul_f32_e32 v34, v46, v34
	v_readlane_b32 s1, v254, 3
	v_exp_f32_e32 v35, v35
	v_mul_f32_e32 v38, v63, v38
	v_cndmask_b32_e64 v211, 0, v34, s[0:1]
	v_readlane_b32 s0, v254, 4
	v_readlane_b32 s1, v254, 5
	v_mul_f32_e32 v35, v47, v35
	v_add_f32_e32 v34, v62, v211
	v_cndmask_b32_e64 v46, 0, v38, s[0:1]
	v_readlane_b32 s0, v254, 6
	v_readlane_b32 s1, v254, 7
	v_add_f32_e32 v34, v34, v210
	v_cvt_pk_f16_f32 v38, v58, v59
	v_cndmask_b32_e64 v63, 0, v35, s[0:1]
	v_add_f32_e32 v35, v46, v63
	v_add_f32_e32 v34, v35, v34
	v_sub_f32_e32 v35, v40, v161
	v_mul_f32_e32 v35, 0x3fb8aa3b, v35
	v_exp_f32_e32 v35, v35
	v_readlane_b32 s0, v254, 8
	v_readlane_b32 s1, v254, 9
	v_cvt_pk_f16_f32 v40, v62, v46
	v_mul_f32_e32 v35, v64, v35
	v_cndmask_b32_e64 v47, 0, v35, s[0:1]
	v_sub_f32_e32 v35, v36, v161
	v_mul_f32_e32 v35, 0x3fb8aa3b, v35
	v_exp_f32_e32 v35, v35
	v_readlane_b32 s0, v254, 10
	v_readlane_b32 s1, v254, 11
	v_cvt_pk_f16_f32 v46, v50, v51
	v_mul_f32_e32 v35, v48, v35
	v_cndmask_b32_e64 v64, 0, v35, s[0:1]
	v_add_f32_e32 v35, v47, v64
	v_add_f32_e32 v34, v35, v34
	v_sub_f32_e32 v35, v41, v161
	v_mul_f32_e32 v35, 0x3fb8aa3b, v35
	v_exp_f32_e32 v35, v35
	v_readlane_b32 s0, v254, 12
	v_readlane_b32 s1, v254, 13
	ds_read_b64_tr_b16 v[50:51],v176 offset:0
	v_mul_f32_e32 v35, v65, v35
	v_cvt_pk_f16_f32 v36, v54, v55
	v_cndmask_b32_e64 v41, 0, v35, s[0:1]
	v_sub_f32_e32 v35, v37, v161
	v_mul_f32_e32 v35, 0x3fb8aa3b, v35
	v_exp_f32_e32 v35, v35
	v_readlane_b32 s0, v254, 14
	v_readlane_b32 s1, v254, 15
	v_cvt_pk_f16_f32 v37, v56, v57
	v_mul_f32_e32 v35, v49, v35
	v_cndmask_b32_e64 v65, 0, v35, s[0:1]
	v_add_f32_e32 v35, v41, v65
	v_cvt_pk_f16_f32 v41, v47, v41
	v_cvt_pk_f16_f32 v47, v52, v53
	ds_read_b64_tr_b16 v[52:53],v176 offset:512
	ds_read_b64_tr_b16 v[54:55],v176 offset:1024
	ds_read_b64_tr_b16 v[56:57],v176 offset:1536
	ds_read_b64_tr_b16 v[58:59],v176 offset:2048
	v_cvt_pk_f16_f32 v39, v60, v61
	ds_read_b64_tr_b16 v[60:61],v176 offset:2560
	v_cvt_pk_f16_f32 v44, v211, v63
	ds_read_b64_tr_b16 v[62:63],v176 offset:3072
	v_cvt_pk_f16_f32 v45, v64, v65
	ds_read_b64_tr_b16 v[64:65],v176 offset:3584
	s_waitcnt lgkmcnt(0)
	v_add_f32_e32 v222, v35, v34
	v_cvt_pk_f16_f32 v34, v218, v219
	v_cvt_pk_f16_f32 v35, v220, v221
	v_cvt_pk_f16_f32 v48, v132, v133
	v_cvt_pk_f16_f32 v49, v134, v135
	v_mfma_f32_32x32x16_f16 v[2:17], v[34:37], v[50:53], v[2:17]
	ds_read_b64_tr_b16 v[50:51],v176 offset:4096
	ds_read_b64_tr_b16 v[52:53],v176 offset:4608
	v_mfma_f32_32x32x16_f16 v[2:17], v[38:41], v[54:57], v[2:17]
	ds_read_b64_tr_b16 v[54:55],v176 offset:5120
	ds_read_b64_tr_b16 v[56:57],v176 offset:5632
	v_mfma_f32_32x32x16_f16 v[2:17], v[46:49], v[58:61], v[2:17]
	ds_read_b64_tr_b16 v[58:59],v176 offset:6144
	ds_read_b64_tr_b16 v[60:61],v176 offset:6656
	v_mfma_f32_32x32x16_f16 v[2:17], v[42:45], v[62:65], v[2:17]
	ds_read_b64_tr_b16 v[62:63],v176 offset:7168
	ds_read_b64_tr_b16 v[64:65],v176 offset:7680
	s_waitcnt lgkmcnt(0)
	v_mfma_f32_32x32x16_f16 v[18:33], v[34:37], v[50:53], v[18:33]
	v_mfma_f32_32x32x16_f16 v[18:33], v[38:41], v[54:57], v[18:33]
	v_mfma_f32_32x32x16_f16 v[18:33], v[46:49], v[58:61], v[18:33]
	v_mfma_f32_32x32x16_f16 v[18:33], v[42:45], v[62:65], v[18:33]
